# removed store-completion waits at gmlp item start, retd start and context-GEMM start (loads no longer wait for the previous segment's stores)
# baseline (speedup 1.0000x reference)
.LBB0_257:
	v_readfirstlane_b32 s22, v140
	s_ashr_i32 s10, s22, 7
	s_ashr_i32 s11, s10, 31
	s_lshl_b64 s[20:21], s[10:11], 15
	v_and_or_b32 v80, s22, 64, v145
	v_lshl_add_u64 v[18:19], v[74:75], 0, s[20:21]
	v_lshlrev_b32_e32 v0, 8, v80
	s_nop 0
	v_or_b32_e32 v22, 0x1000, v0
	v_mov_b32_e32 v23, v1
	s_nop 0
	v_lshl_add_u64 v[14:15], v[18:19], 0, s[34:35]
	v_lshl_add_u64 v[2:3], v[18:19], 0, v[22:23]
	v_or_b32_e32 v26, 0x2000, v0
	v_mov_b32_e32 v27, v1
	v_lshl_add_u64 v[6:7], v[14:15], 0, v[22:23]
	v_lshl_add_u64 v[20:21], v[18:19], 0, v[0:1]
	global_load_dwordx4 v[54:57], v[2:3], off
	v_or_b32_e32 v0, 0x3000, v0
	global_load_dwordx4 v[6:9], v[6:7], off
	v_lshl_add_u64 v[2:3], v[18:19], 0, v[26:27]
	v_lshl_add_u64 v[10:11], v[14:15], 0, v[26:27]
	s_mov_b64 s[20:21], 0xc0
	v_mov_b64_e32 v[82:83], s[72:73]
	global_load_dwordx4 v[58:61], v[2:3], off
	v_lshl_add_u64 v[14:15], v[14:15], 0, v[0:1]
	global_load_dwordx4 v[10:13], v[10:11], off
	v_lshl_add_u64 v[2:3], v[18:19], 0, v[0:1]
	v_lshl_add_u64 v[30:31], v[18:19], 0, s[20:21]
	v_mad_i64_i32 v[66:67], s[20:21], v87, s64, v[82:83]
	global_load_dwordx4 v[62:65], v[2:3], off
	v_lshl_add_u64 v[66:67], v[76:77], 1, v[66:67]
	global_load_dwordx4 v[14:17], v[14:15], off
	v_lshl_add_u64 v[2:3], v[18:19], 0, 64
	s_mov_b64 s[20:21], 0x1000
	v_lshl_add_u64 v[4:5], v[2:3], 0, v[22:23]
	v_lshl_add_u64 v[96:97], v[66:67], 0, s[20:21]
	v_add_co_u32_e32 v66, vcc, s26, v66
	global_load_dwordx4 v[50:53], v[20:21], off
	global_load_dwordx4 v[38:41], v[4:5], off
	v_lshl_add_u64 v[4:5], v[2:3], 0, v[26:27]
	v_lshl_add_u64 v[2:3], v[2:3], 0, v[0:1]
	v_lshl_add_u64 v[22:23], v[30:31], 0, v[22:23]
	v_lshl_add_u64 v[26:27], v[30:31], 0, v[26:27]
	v_lshl_add_u64 v[30:31], v[30:31], 0, v[0:1]
	v_addc_co_u32_e32 v67, vcc, 0, v67, vcc
	global_load_dwordx4 v[34:37], v[20:21], off offset:64
	global_load_dwordx4 v[42:45], v[4:5], off
	global_load_dwordx4 v[46:49], v[2:3], off
	s_mul_i32 s11, s10, 0x4800
	global_load_dwordx4 v[2:5], v[20:21], off offset:128
	s_add_i32 s16, s16, s96
	global_load_dwordx4 v[18:21], v[20:21], off offset:192
	v_add_u32_e32 v87, s23, v87
	global_load_dwordx4 v[22:25], v[22:23], off
	s_nop 0
	global_load_dwordx4 v[26:29], v[26:27], off
	s_nop 0
	global_load_dwordx4 v[30:33], v[30:31], off
	s_nop 0
	global_load_dwordx4 v[66:69], v[66:67], off
	s_nop 0
	global_load_dwordx4 v[70:73], v[96:97], off offset:48
	global_load_dwordx4 v[88:91], v[96:97], off offset:32
	global_load_dwordx4 v[92:95], v[96:97], off offset:16
	s_waitcnt vmcnt(3)
	v_lshlrev_b32_e32 v150, 16, v66
	v_and_b32_e32 v149, 0xffff0000, v66
	v_lshlrev_b32_e32 v148, 16, v67
	v_and_b32_e32 v146, 0xffff0000, v67
	v_lshlrev_b32_e32 v137, 16, v68
	v_and_b32_e32 v136, 0xffff0000, v68
	v_lshlrev_b32_e32 v135, 16, v69
	v_and_b32_e32 v134, 0xffff0000, v69
	s_waitcnt vmcnt(0)
	v_lshlrev_b32_e32 v133, 16, v92
	v_and_b32_e32 v132, 0xffff0000, v92
	v_lshlrev_b32_e32 v131, 16, v93
	v_and_b32_e32 v130, 0xffff0000, v93
	v_lshlrev_b32_e32 v129, 16, v94
	v_and_b32_e32 v128, 0xffff0000, v94
	v_lshlrev_b32_e32 v127, 16, v95
	v_and_b32_e32 v126, 0xffff0000, v95
	v_lshlrev_b32_e32 v125, 16, v88
	v_and_b32_e32 v124, 0xffff0000, v88
	v_lshlrev_b32_e32 v123, 16, v89
	v_and_b32_e32 v122, 0xffff0000, v89
	v_lshlrev_b32_e32 v121, 16, v90
	v_and_b32_e32 v120, 0xffff0000, v90
	v_lshlrev_b32_e32 v119, 16, v91
	v_and_b32_e32 v118, 0xffff0000, v91
	v_lshlrev_b32_e32 v117, 16, v70
	v_and_b32_e32 v116, 0xffff0000, v70
	v_lshlrev_b32_e32 v115, 16, v71
	v_and_b32_e32 v114, 0xffff0000, v71
	v_lshlrev_b32_e32 v113, 16, v72
	v_and_b32_e32 v112, 0xffff0000, v72
	v_lshlrev_b32_e32 v111, 16, v73
	v_and_b32_e32 v110, 0xffff0000, v73
	global_load_dwordx4 v[66:69], v[96:97], off offset:112
	global_load_dwordx4 v[70:73], v[96:97], off offset:96
	global_load_dwordx4 v[88:91], v[96:97], off offset:80
	global_load_dwordx4 v[92:95], v[96:97], off offset:64
	s_waitcnt vmcnt(3)
	v_and_b32_e32 v0, 0xffff0000, v66
	s_waitcnt vmcnt(2)
	v_lshlrev_b32_e32 v81, 16, v73
	s_waitcnt vmcnt(1)
	v_lshlrev_b32_e32 v101, 16, v88
	v_and_b32_e32 v100, 0xffff0000, v88
	v_lshlrev_b32_e32 v99, 16, v89
	v_and_b32_e32 v98, 0xffff0000, v89
	v_lshlrev_b32_e32 v89, 16, v72
	v_and_b32_e32 v88, 0xffff0000, v72
	v_lshlrev_b32_e32 v72, 16, v66
	v_add_f32_e32 v66, 0, v150
	v_add_f32_e32 v66, v66, v149
	v_add_f32_e32 v66, v66, v148
	v_add_f32_e32 v66, v66, v146
	v_add_f32_e32 v66, v66, v137
	v_add_f32_e32 v66, v66, v136
	v_add_f32_e32 v66, v66, v135
	v_add_f32_e32 v66, v66, v134
	v_add_f32_e32 v66, v66, v133
	v_add_f32_e32 v66, v66, v132
	v_add_f32_e32 v66, v66, v131
	v_add_f32_e32 v66, v66, v130
	v_add_f32_e32 v66, v66, v129
	v_add_f32_e32 v66, v66, v128
	v_add_f32_e32 v66, v66, v127
	v_add_f32_e32 v66, v66, v126
	v_add_f32_e32 v66, v66, v125
	v_add_f32_e32 v66, v66, v124
	v_add_f32_e32 v66, v66, v123
	v_add_f32_e32 v66, v66, v122
	v_add_f32_e32 v66, v66, v121
	v_add_f32_e32 v66, v66, v120
	v_add_f32_e32 v66, v66, v119
	v_add_f32_e32 v66, v66, v118
	v_add_f32_e32 v66, v66, v117
	v_add_f32_e32 v66, v66, v116
	v_add_f32_e32 v66, v66, v115
	v_add_f32_e32 v66, v66, v114
	v_add_f32_e32 v66, v66, v113
	v_add_f32_e32 v66, v66, v112
	v_add_f32_e32 v66, v66, v111
	s_waitcnt vmcnt(0)
	v_lshlrev_b32_e32 v109, 16, v92
	v_add_f32_e32 v66, v66, v110
	v_and_b32_e32 v108, 0xffff0000, v92
	v_add_f32_e32 v66, v66, v109
	v_lshlrev_b32_e32 v107, 16, v93
	v_add_f32_e32 v66, v66, v108
	v_and_b32_e32 v106, 0xffff0000, v93
	v_add_f32_e32 v66, v66, v107
	v_lshlrev_b32_e32 v105, 16, v94
	v_add_f32_e32 v66, v66, v106
	v_and_b32_e32 v104, 0xffff0000, v94
	v_add_f32_e32 v66, v66, v105
	v_lshlrev_b32_e32 v103, 16, v95
	v_add_f32_e32 v66, v66, v104
	v_and_b32_e32 v102, 0xffff0000, v95
	v_add_f32_e32 v66, v66, v103
	v_add_f32_e32 v66, v66, v102
	v_add_f32_e32 v66, v66, v101
	v_add_f32_e32 v66, v66, v100
	v_add_f32_e32 v66, v66, v99
	v_lshlrev_b32_e32 v97, 16, v90
	v_add_f32_e32 v66, v66, v98
	v_and_b32_e32 v96, 0xffff0000, v90
	v_add_f32_e32 v66, v66, v97
	v_lshlrev_b32_e32 v95, 16, v91
	v_add_f32_e32 v66, v66, v96
	v_and_b32_e32 v94, 0xffff0000, v91
	v_add_f32_e32 v66, v66, v95
	v_lshlrev_b32_e32 v93, 16, v70
	v_add_f32_e32 v66, v66, v94
	v_and_b32_e32 v92, 0xffff0000, v70
	v_add_f32_e32 v66, v66, v93
	v_lshlrev_b32_e32 v91, 16, v71
	v_add_f32_e32 v66, v66, v92
	v_and_b32_e32 v90, 0xffff0000, v71
	v_add_f32_e32 v66, v66, v91
	v_add_f32_e32 v66, v66, v90
	v_add_f32_e32 v66, v66, v89
	v_add_f32_e32 v66, v66, v88
	v_and_b32_e32 v73, 0xffff0000, v73
	v_add_f32_e32 v66, v66, v81
	v_add_f32_e32 v66, v66, v73
	v_add_f32_e32 v66, v66, v72
	v_add_f32_e32 v70, v66, v0
	v_and_b32_e32 v66, 0xffff0000, v67
	v_lshlrev_b32_e32 v67, 16, v67
	v_and_b32_e32 v156, 0xffff0000, v68
	v_lshlrev_b32_e32 v157, 16, v68
	v_add_f32_e32 v68, v70, v67
	v_add_f32_e32 v68, v68, v66
	v_add_f32_e32 v68, v68, v157
	v_lshlrev_b32_e32 v153, 16, v69
	v_add_f32_e32 v68, v68, v156
	v_and_b32_e32 v152, 0xffff0000, v69
	v_add_f32_e32 v68, v68, v153
	v_add_f32_e32 v68, v68, v152
	v_fmac_f32_e32 v149, 0xbc800000, v68
	v_fmac_f32_e32 v150, 0xbc800000, v68
	v_mul_f32_e32 v69, v149, v149
	v_fmac_f32_e32 v69, v150, v150
	v_fmac_f32_e32 v148, 0xbc800000, v68
	v_fmac_f32_e32 v69, v148, v148
	v_fmac_f32_e32 v146, 0xbc800000, v68
	v_fmac_f32_e32 v69, v146, v146
	v_fmac_f32_e32 v137, 0xbc800000, v68
	v_fmac_f32_e32 v69, v137, v137
	v_fmac_f32_e32 v136, 0xbc800000, v68
	v_fmac_f32_e32 v69, v136, v136
	v_fmac_f32_e32 v135, 0xbc800000, v68
	v_fmac_f32_e32 v69, v135, v135
	v_fmac_f32_e32 v134, 0xbc800000, v68
	v_fmac_f32_e32 v69, v134, v134
	v_fmac_f32_e32 v133, 0xbc800000, v68
	v_fmac_f32_e32 v69, v133, v133
	v_fmac_f32_e32 v132, 0xbc800000, v68
	v_fmac_f32_e32 v69, v132, v132
	v_fmac_f32_e32 v131, 0xbc800000, v68
	v_fmac_f32_e32 v69, v131, v131
	v_fmac_f32_e32 v130, 0xbc800000, v68
	v_fmac_f32_e32 v69, v130, v130
	v_fmac_f32_e32 v129, 0xbc800000, v68
	v_fmac_f32_e32 v69, v129, v129
	v_fmac_f32_e32 v128, 0xbc800000, v68
	v_fmac_f32_e32 v69, v128, v128
	v_fmac_f32_e32 v127, 0xbc800000, v68
	v_fmac_f32_e32 v69, v127, v127
	v_fmac_f32_e32 v126, 0xbc800000, v68
	v_fmac_f32_e32 v69, v126, v126
	v_fmac_f32_e32 v125, 0xbc800000, v68
	v_fmac_f32_e32 v69, v125, v125
	v_fmac_f32_e32 v124, 0xbc800000, v68
	v_fmac_f32_e32 v69, v124, v124
	v_fmac_f32_e32 v123, 0xbc800000, v68
	v_fmac_f32_e32 v69, v123, v123
	v_fmac_f32_e32 v122, 0xbc800000, v68
	v_fmac_f32_e32 v69, v122, v122
	v_fmac_f32_e32 v121, 0xbc800000, v68
	v_fmac_f32_e32 v69, v121, v121
	v_fmac_f32_e32 v120, 0xbc800000, v68
	v_fmac_f32_e32 v69, v120, v120
	v_fmac_f32_e32 v119, 0xbc800000, v68
	v_fmac_f32_e32 v69, v119, v119
	v_fmac_f32_e32 v118, 0xbc800000, v68
	v_fmac_f32_e32 v69, v118, v118
	v_fmac_f32_e32 v117, 0xbc800000, v68
	v_fmac_f32_e32 v69, v117, v117
	v_fmac_f32_e32 v116, 0xbc800000, v68
	v_fmac_f32_e32 v69, v116, v116
	v_fmac_f32_e32 v115, 0xbc800000, v68
	v_fmac_f32_e32 v69, v115, v115
	v_fmac_f32_e32 v114, 0xbc800000, v68
	v_fmac_f32_e32 v69, v114, v114
	v_fmac_f32_e32 v113, 0xbc800000, v68
	v_fmac_f32_e32 v69, v113, v113
	v_fmac_f32_e32 v112, 0xbc800000, v68
	v_fmac_f32_e32 v69, v112, v112
	v_fmac_f32_e32 v111, 0xbc800000, v68
	v_fmac_f32_e32 v69, v111, v111
	v_fmac_f32_e32 v110, 0xbc800000, v68
	v_fmac_f32_e32 v69, v110, v110
	v_fmac_f32_e32 v109, 0xbc800000, v68
	v_fmac_f32_e32 v69, v109, v109
	v_fmac_f32_e32 v108, 0xbc800000, v68
	v_fmac_f32_e32 v69, v108, v108
	v_fmac_f32_e32 v107, 0xbc800000, v68
	v_fmac_f32_e32 v69, v107, v107
	v_fmac_f32_e32 v106, 0xbc800000, v68
	v_fmac_f32_e32 v69, v106, v106
	v_fmac_f32_e32 v105, 0xbc800000, v68
	v_fmac_f32_e32 v69, v105, v105
	v_fmac_f32_e32 v104, 0xbc800000, v68
	v_fmac_f32_e32 v69, v104, v104
	v_fmac_f32_e32 v103, 0xbc800000, v68
	v_fmac_f32_e32 v69, v103, v103
	v_fmac_f32_e32 v102, 0xbc800000, v68
	v_fmac_f32_e32 v69, v102, v102
	v_fmac_f32_e32 v101, 0xbc800000, v68
	v_fmac_f32_e32 v69, v101, v101
	v_fmac_f32_e32 v100, 0xbc800000, v68
	v_fmac_f32_e32 v69, v100, v100
	v_fmac_f32_e32 v99, 0xbc800000, v68
	v_fmac_f32_e32 v69, v99, v99
	v_fmac_f32_e32 v98, 0xbc800000, v68
	v_fmac_f32_e32 v69, v98, v98
	v_fmac_f32_e32 v97, 0xbc800000, v68
	v_fmac_f32_e32 v69, v97, v97
	v_fmac_f32_e32 v96, 0xbc800000, v68
	v_fmac_f32_e32 v69, v96, v96
	v_fmac_f32_e32 v95, 0xbc800000, v68
	v_fmac_f32_e32 v69, v95, v95
	v_fmac_f32_e32 v94, 0xbc800000, v68
	v_fmac_f32_e32 v69, v94, v94
	v_fmac_f32_e32 v93, 0xbc800000, v68
	v_fmac_f32_e32 v69, v93, v93
	v_fmac_f32_e32 v92, 0xbc800000, v68
	v_fmac_f32_e32 v69, v92, v92
	v_fmac_f32_e32 v91, 0xbc800000, v68
	v_fmac_f32_e32 v69, v91, v91
	v_fmac_f32_e32 v90, 0xbc800000, v68
	v_fmac_f32_e32 v69, v90, v90
	v_fmac_f32_e32 v89, 0xbc800000, v68
	v_fmac_f32_e32 v69, v89, v89
	v_fmac_f32_e32 v88, 0xbc800000, v68
	v_fmac_f32_e32 v69, v88, v88
	v_fmac_f32_e32 v81, 0xbc800000, v68
	v_fmac_f32_e32 v69, v81, v81
	v_fmac_f32_e32 v73, 0xbc800000, v68
	v_mul_f32_e32 v158, 0x3c800000, v68
	v_fmac_f32_e32 v69, v73, v73
	v_fmac_f32_e32 v72, 0xbc800000, v68
	v_fmac_f32_e32 v69, v72, v72
	v_fmac_f32_e32 v0, 0xbc800000, v68
	v_pk_add_f32 v[70:71], v[66:67], v[158:159] op_sel_hi:[1,0] neg_lo:[0,1] neg_hi:[0,1]
	v_fmac_f32_e32 v69, v0, v0
	v_pk_mul_f32 v[66:67], v[70:71], v[70:71]
	s_nop 0
	v_add_f32_e32 v67, v67, v69
	v_pk_add_f32 v[68:69], v[156:157], v[158:159] op_sel_hi:[1,0] neg_lo:[0,1] neg_hi:[0,1]
	v_add_f32_e32 v151, v66, v67
	v_pk_mul_f32 v[66:67], v[68:69], v[68:69]
	s_nop 0
	v_add_f32_e32 v67, v67, v151
	v_add_f32_e32 v151, v66, v67
	v_pk_add_f32 v[66:67], v[152:153], v[158:159] op_sel_hi:[1,0] neg_lo:[0,1] neg_hi:[0,1]
	global_load_dwordx4 v[156:159], v[78:79], off offset:16
	global_load_dwordx4 v[160:163], v[78:79], off
	global_load_dwordx4 v[196:199], v[78:79], off offset:48
	global_load_dwordx4 v[200:203], v[78:79], off offset:32
	global_load_dwordx4 v[204:207], v[78:79], off offset:80
	global_load_dwordx4 v[208:211], v[78:79], off offset:64
	global_load_dwordx4 v[212:215], v[78:79], off offset:112
	global_load_dwordx4 v[216:219], v[78:79], off offset:96
	global_load_dwordx4 v[220:223], v[78:79], off offset:144
	global_load_dwordx4 v[224:227], v[78:79], off offset:128
	global_load_dwordx4 v[228:231], v[78:79], off offset:176
	global_load_dwordx4 v[232:235], v[78:79], off offset:160
	global_load_dwordx4 v[236:239], v[78:79], off offset:208
	global_load_dwordx4 v[240:243], v[78:79], off offset:192
	global_load_dwordx4 v[244:247], v[78:79], off offset:240
	global_load_dwordx4 v[248:251], v[78:79], off offset:224
	v_pk_mul_f32 v[152:153], v[66:67], v[66:67]
	s_nop 0
	v_add_f32_e32 v151, v153, v151
	v_add_f32_e32 v151, v152, v151
	v_fmamk_f32 v151, v151, 0x3c800000, v177
	v_rsq_f32_e32 v151, v151
	s_nop 0
	v_mul_f32_e32 v150, v150, v151
	v_mul_f32_e32 v149, v149, v151
	v_mul_f32_e32 v148, v148, v151
	v_mul_f32_e32 v146, v146, v151
	v_mul_f32_e32 v137, v137, v151
	v_mul_f32_e32 v136, v136, v151
	v_mul_f32_e32 v135, v135, v151
	v_mul_f32_e32 v134, v134, v151
	v_mul_f32_e32 v133, v133, v151
	v_mul_f32_e32 v132, v132, v151
	v_mul_f32_e32 v131, v131, v151
	v_mul_f32_e32 v130, v130, v151
	v_mul_f32_e32 v129, v129, v151
	v_mul_f32_e32 v128, v128, v151
	v_mul_f32_e32 v127, v127, v151
	v_mul_f32_e32 v126, v126, v151
	v_mul_f32_e32 v125, v125, v151
	v_mul_f32_e32 v124, v124, v151
	v_mul_f32_e32 v123, v123, v151
	v_mul_f32_e32 v122, v122, v151
	v_mul_f32_e32 v121, v121, v151
	v_mul_f32_e32 v120, v120, v151
	v_mul_f32_e32 v119, v119, v151
	v_mul_f32_e32 v118, v118, v151
	v_mul_f32_e32 v117, v117, v151
	v_mul_f32_e32 v116, v116, v151
	v_mul_f32_e32 v115, v115, v151
	v_mul_f32_e32 v114, v114, v151
	v_mul_f32_e32 v113, v113, v151
	v_mul_f32_e32 v112, v112, v151
	v_mul_f32_e32 v111, v111, v151
	v_mul_f32_e32 v110, v110, v151
	v_mul_f32_e32 v109, v109, v151
	v_mul_f32_e32 v108, v108, v151
	v_mul_f32_e32 v107, v107, v151
	v_mul_f32_e32 v106, v106, v151
	v_mul_f32_e32 v105, v105, v151
	v_mul_f32_e32 v104, v104, v151
	v_mul_f32_e32 v103, v103, v151
	v_mul_f32_e32 v102, v102, v151
	v_mul_f32_e32 v101, v101, v151
	v_mul_f32_e32 v100, v100, v151
	v_mul_f32_e32 v99, v99, v151
	v_mul_f32_e32 v98, v98, v151
	v_mul_f32_e32 v97, v97, v151
	v_mul_f32_e32 v96, v96, v151
	v_mul_f32_e32 v95, v95, v151
	v_mul_f32_e32 v94, v94, v151
	v_mul_f32_e32 v93, v93, v151
	v_mul_f32_e32 v92, v92, v151
	v_mul_f32_e32 v91, v91, v151
	v_mul_f32_e32 v90, v90, v151
	v_mul_f32_e32 v89, v89, v151
	v_mul_f32_e32 v88, v88, v151
	v_mul_f32_e32 v81, v81, v151
	v_mul_f32_e32 v73, v73, v151
	v_mul_f32_e32 v0, v0, v151
	v_mul_f32_e32 v72, v72, v151
	v_mul_f32_e32 v70, v70, v151
	v_mul_f32_e32 v68, v68, v151
	v_mul_f32_e32 v66, v66, v151
	s_waitcnt vmcnt(15)
	v_mul_f32_e32 v137, v156, v137
	s_waitcnt vmcnt(14)
	v_mul_f32_e32 v150, v160, v150
	v_mul_f32_e32 v149, v161, v149
	v_cvt_pk_bf16_f32 v160, v150, v149
	v_mul_f32_e32 v148, v162, v148
	v_mul_f32_e32 v146, v163, v146
	v_cvt_pk_bf16_f32 v161, v148, v146
	v_mul_f32_e32 v136, v157, v136
	v_cvt_pk_bf16_f32 v162, v137, v136
	v_mul_f32_e32 v135, v158, v135
	v_mul_f32_e32 v134, v159, v134
	v_cvt_pk_bf16_f32 v163, v135, v134
	ds_write_b128 v86, v[160:163]
	s_waitcnt vmcnt(13)
	v_mul_f32_e32 v129, v196, v129
	s_waitcnt vmcnt(12)
	v_mul_f32_e32 v133, v200, v133
	v_mul_f32_e32 v132, v201, v132
	v_cvt_pk_bf16_f32 v132, v133, v132
	v_mul_f32_e32 v131, v202, v131
	v_mul_f32_e32 v130, v203, v130
	v_cvt_pk_bf16_f32 v133, v131, v130
	v_mul_f32_e32 v128, v197, v128
	v_cvt_pk_bf16_f32 v134, v129, v128
	v_mul_f32_e32 v127, v198, v127
	v_mul_f32_e32 v126, v199, v126
	v_cvt_pk_bf16_f32 v135, v127, v126
	ds_write_b128 v86, v[132:135] offset:16
	s_waitcnt vmcnt(11)
	v_mul_f32_e32 v121, v204, v121
	s_waitcnt vmcnt(10)
	v_mul_f32_e32 v125, v208, v125
	v_mul_f32_e32 v124, v209, v124
	v_cvt_pk_bf16_f32 v124, v125, v124
	v_mul_f32_e32 v123, v210, v123
	v_mul_f32_e32 v122, v211, v122
	v_cvt_pk_bf16_f32 v125, v123, v122
	v_mul_f32_e32 v120, v205, v120
	v_cvt_pk_bf16_f32 v126, v121, v120
	v_mul_f32_e32 v119, v206, v119
	v_mul_f32_e32 v118, v207, v118
	v_cvt_pk_bf16_f32 v127, v119, v118
	ds_write_b128 v86, v[124:127] offset:32
	s_waitcnt vmcnt(9)
	v_mul_f32_e32 v113, v212, v113
	s_waitcnt vmcnt(8)
	v_mul_f32_e32 v117, v216, v117
	v_mul_f32_e32 v116, v217, v116
	v_cvt_pk_bf16_f32 v116, v117, v116
	v_mul_f32_e32 v115, v218, v115
	v_mul_f32_e32 v114, v219, v114
	v_cvt_pk_bf16_f32 v117, v115, v114
	v_mul_f32_e32 v112, v213, v112
	v_cvt_pk_bf16_f32 v118, v113, v112
	v_mul_f32_e32 v111, v214, v111
	v_mul_f32_e32 v110, v215, v110
	v_cvt_pk_bf16_f32 v119, v111, v110
	ds_write_b128 v86, v[116:119] offset:48
	s_waitcnt vmcnt(7)
	v_mul_f32_e32 v105, v220, v105
	s_waitcnt vmcnt(6)
	v_mul_f32_e32 v109, v224, v109
	v_mul_f32_e32 v108, v225, v108
	v_cvt_pk_bf16_f32 v108, v109, v108
	v_mul_f32_e32 v107, v226, v107
	v_mul_f32_e32 v106, v227, v106
	v_cvt_pk_bf16_f32 v109, v107, v106
	v_mul_f32_e32 v104, v221, v104
	v_cvt_pk_bf16_f32 v110, v105, v104
	v_mul_f32_e32 v103, v222, v103
	v_mul_f32_e32 v102, v223, v102
	v_cvt_pk_bf16_f32 v111, v103, v102
	ds_write_b128 v86, v[108:111] offset:64
	s_waitcnt vmcnt(5)
	v_mul_f32_e32 v97, v228, v97
	s_waitcnt vmcnt(4)
	v_mul_f32_e32 v101, v232, v101
	v_mul_f32_e32 v100, v233, v100
	v_cvt_pk_bf16_f32 v100, v101, v100
	v_mul_f32_e32 v99, v234, v99
	v_mul_f32_e32 v98, v235, v98
	v_cvt_pk_bf16_f32 v101, v99, v98
	v_mul_f32_e32 v96, v229, v96
	v_cvt_pk_bf16_f32 v102, v97, v96
	v_mul_f32_e32 v95, v230, v95
	v_mul_f32_e32 v94, v231, v94
	v_cvt_pk_bf16_f32 v103, v95, v94
	ds_write_b128 v86, v[100:103] offset:80
	s_waitcnt vmcnt(3)
	v_mul_f32_e32 v89, v236, v89
	s_waitcnt vmcnt(2)
	v_mul_f32_e32 v93, v240, v93
	v_mul_f32_e32 v92, v241, v92
	v_cvt_pk_bf16_f32 v92, v93, v92
	v_mul_f32_e32 v91, v242, v91
	v_mul_f32_e32 v90, v243, v90
	v_cvt_pk_bf16_f32 v93, v91, v90
	v_mul_f32_e32 v88, v237, v88
	v_cvt_pk_bf16_f32 v94, v89, v88
	v_mul_f32_e32 v81, v238, v81
	v_mul_f32_e32 v73, v239, v73
	v_cvt_pk_bf16_f32 v95, v81, v73
	ds_write_b128 v86, v[92:95] offset:96
	v_mov_b32_e32 v81, v1
	s_waitcnt vmcnt(1)
	v_mul_f32_e32 v68, v245, v68
	s_waitcnt vmcnt(0)
	v_mul_f32_e32 v0, v249, v0
	v_mul_f32_e32 v72, v248, v72
	v_cvt_pk_bf16_f32 v92, v72, v0
	v_mul_f32_e32 v0, v71, v151
	v_mul_f32_e32 v0, v250, v0
	v_mul_f32_e32 v70, v251, v70
	v_cvt_pk_bf16_f32 v93, v0, v70
	v_mul_f32_e32 v0, v69, v151
	v_mul_f32_e32 v0, v244, v0
	v_cvt_pk_bf16_f32 v94, v0, v68
	v_mul_f32_e32 v0, v67, v151
	v_mul_f32_e32 v0, v246, v0
	v_mul_f32_e32 v66, v247, v66
	v_cvt_pk_bf16_f32 v95, v0, v66
	v_add_u32_e32 v0, s11, v84
	ds_write_b128 v86, v[92:95] offset:112
	s_waitcnt lgkmcnt(0)
	s_barrier
	ds_read_b64_tr_b16 v[68:69], v0 offset:576
	ds_read_b64_tr_b16 v[66:67], v0
	ds_read_b64_tr_b16 v[70:71], v0 offset:32
	ds_read_b64_tr_b16 v[72:73], v0 offset:608
	ds_read_b64_tr_b16 v[88:89], v0 offset:64
	ds_read_b64_tr_b16 v[90:91], v0 offset:640
	ds_read_b64_tr_b16 v[92:93], v0 offset:96
	ds_read_b64_tr_b16 v[94:95], v0 offset:672
	s_waitcnt lgkmcnt(6)
	v_mfma_f32_16x16x32_bf16 v[96:99], v[66:69], v[50:53], 0
	s_and_b32 s11, s22, 0xffffff80
	v_mfma_f32_16x16x32_bf16 v[100:103], v[66:69], v[54:57], 0
	v_mfma_f32_16x16x32_bf16 v[104:107], v[66:69], v[58:61], 0
	v_mfma_f32_16x16x32_bf16 v[66:69], v[66:69], v[62:65], 0
	s_waitcnt lgkmcnt(4)
	v_mfma_f32_16x16x32_bf16 v[108:111], v[70:73], v[50:53], 0
	v_mfma_f32_16x16x32_bf16 v[112:115], v[70:73], v[54:57], 0
	v_mfma_f32_16x16x32_bf16 v[116:119], v[70:73], v[58:61], 0
	v_mfma_f32_16x16x32_bf16 v[70:73], v[70:73], v[62:65], 0
	s_waitcnt lgkmcnt(2)
	v_mfma_f32_16x16x32_bf16 v[120:123], v[88:91], v[50:53], 0
	v_mfma_f32_16x16x32_bf16 v[124:127], v[88:91], v[54:57], 0
	v_mfma_f32_16x16x32_bf16 v[128:131], v[88:91], v[58:61], 0
	v_mfma_f32_16x16x32_bf16 v[88:91], v[88:91], v[62:65], 0
	s_waitcnt lgkmcnt(0)
	v_mfma_f32_16x16x32_bf16 v[50:53], v[92:95], v[50:53], 0
	v_mfma_f32_16x16x32_bf16 v[54:57], v[92:95], v[54:57], 0
	v_mfma_f32_16x16x32_bf16 v[58:61], v[92:95], v[58:61], 0
	v_mfma_f32_16x16x32_bf16 v[62:65], v[92:95], v[62:65], 0
	ds_read_b64_tr_b16 v[92:93], v0 offset:4608
	ds_read_b64_tr_b16 v[94:95], v0 offset:5184
	ds_read_b64_tr_b16 v[132:133], v0 offset:4640
	ds_read_b64_tr_b16 v[134:135], v0 offset:5216
	ds_read_b64_tr_b16 v[148:149], v0 offset:4672
	ds_read_b64_tr_b16 v[150:151], v0 offset:5248
	ds_read_b64_tr_b16 v[156:157], v0 offset:4704
	ds_read_b64_tr_b16 v[158:159], v0 offset:5280
	s_waitcnt lgkmcnt(6)
	v_mfma_f32_16x16x32_bf16 v[96:99], v[92:95], v[34:37], v[96:99]
	v_mfma_f32_16x16x32_bf16 v[100:103], v[92:95], v[38:41], v[100:103]
	v_mfma_f32_16x16x32_bf16 v[104:107], v[92:95], v[42:45], v[104:107]
	v_mfma_f32_16x16x32_bf16 v[66:69], v[92:95], v[46:49], v[66:69]
	s_waitcnt lgkmcnt(4)
	v_mfma_f32_16x16x32_bf16 v[92:95], v[132:135], v[34:37], v[108:111]
	v_mfma_f32_16x16x32_bf16 v[108:111], v[132:135], v[38:41], v[112:115]
	v_mfma_f32_16x16x32_bf16 v[112:115], v[132:135], v[42:45], v[116:119]
	v_mfma_f32_16x16x32_bf16 v[70:73], v[132:135], v[46:49], v[70:73]
	s_waitcnt lgkmcnt(2)
	v_mfma_f32_16x16x32_bf16 v[116:119], v[148:151], v[34:37], v[120:123]
	v_mfma_f32_16x16x32_bf16 v[120:123], v[148:151], v[38:41], v[124:127]
	v_mfma_f32_16x16x32_bf16 v[124:127], v[148:151], v[42:45], v[128:131]
	v_mfma_f32_16x16x32_bf16 v[88:91], v[148:151], v[46:49], v[88:91]
	s_waitcnt lgkmcnt(0)
	v_mfma_f32_16x16x32_bf16 v[34:37], v[156:159], v[34:37], v[50:53]
	v_mfma_f32_16x16x32_bf16 v[38:41], v[156:159], v[38:41], v[54:57]
	v_mfma_f32_16x16x32_bf16 v[42:45], v[156:159], v[42:45], v[58:61]
	v_mfma_f32_16x16x32_bf16 v[46:49], v[156:159], v[46:49], v[62:65]
	ds_read_b64_tr_b16 v[50:51], v0 offset:9216
	ds_read_b64_tr_b16 v[52:53], v0 offset:9792
	ds_read_b64_tr_b16 v[54:55], v0 offset:9248
	ds_read_b64_tr_b16 v[56:57], v0 offset:9824
	ds_read_b64_tr_b16 v[58:59], v0 offset:9280
	ds_read_b64_tr_b16 v[60:61], v0 offset:9856
	ds_read_b64_tr_b16 v[62:63], v0 offset:9312
	ds_read_b64_tr_b16 v[64:65], v0 offset:9888
	s_waitcnt lgkmcnt(6)
	v_mfma_f32_16x16x32_bf16 v[96:99], v[50:53], v[2:5], v[96:99]
	v_mfma_f32_16x16x32_bf16 v[100:103], v[50:53], v[6:9], v[100:103]
	v_mfma_f32_16x16x32_bf16 v[104:107], v[50:53], v[10:13], v[104:107]
	v_mfma_f32_16x16x32_bf16 v[50:53], v[50:53], v[14:17], v[66:69]
	s_waitcnt lgkmcnt(4)
	v_mfma_f32_16x16x32_bf16 v[66:69], v[54:57], v[2:5], v[92:95]
	v_mfma_f32_16x16x32_bf16 v[92:95], v[54:57], v[6:9], v[108:111]
	v_mfma_f32_16x16x32_bf16 v[108:111], v[54:57], v[10:13], v[112:115]
	s_waitcnt lgkmcnt(2)
	v_mfma_f32_16x16x32_bf16 v[116:119], v[58:61], v[2:5], v[116:119]
	v_mfma_f32_16x16x32_bf16 v[120:123], v[58:61], v[6:9], v[120:123]
	v_mfma_f32_16x16x32_bf16 v[124:127], v[58:61], v[10:13], v[124:127]
	v_mfma_f32_16x16x32_bf16 v[58:61], v[58:61], v[14:17], v[88:91]
	s_waitcnt lgkmcnt(0)
	v_mfma_f32_16x16x32_bf16 v[88:91], v[62:65], v[6:9], v[38:41]
	v_mfma_f32_16x16x32_bf16 v[128:131], v[62:65], v[10:13], v[42:45]
	ds_read_b64_tr_b16 v[6:7], v0 offset:13824
	ds_read_b64_tr_b16 v[8:9], v0 offset:14400
	ds_read_b64_tr_b16 v[10:11], v0 offset:13856
	ds_read_b64_tr_b16 v[12:13], v0 offset:14432
	ds_read_b64_tr_b16 v[148:149], v0 offset:13888
	ds_read_b64_tr_b16 v[150:151], v0 offset:14464
	ds_read_b64_tr_b16 v[156:157], v0 offset:13920
	ds_read_b64_tr_b16 v[158:159], v0 offset:14496
	v_mfma_f32_16x16x32_bf16 v[2:5], v[62:65], v[2:5], v[34:37]
	v_mfma_f32_16x16x32_bf16 v[112:115], v[54:57], v[14:17], v[70:73]
	v_mfma_f32_16x16x32_bf16 v[132:135], v[62:65], v[14:17], v[46:49]
	s_waitcnt lgkmcnt(6)
	v_mfma_f32_16x16x32_bf16 v[70:73], v[6:9], v[18:21], v[96:99]
	v_mfma_f32_16x16x32_bf16 v[54:57], v[6:9], v[22:25], v[100:103]
	v_mfma_f32_16x16x32_bf16 v[42:45], v[6:9], v[26:29], v[104:107]
	v_mfma_f32_16x16x32_bf16 v[14:17], v[6:9], v[30:33], v[50:53]
	s_waitcnt lgkmcnt(4)
	v_mfma_f32_16x16x32_bf16 v[66:69], v[10:13], v[18:21], v[66:69]
	v_mfma_f32_16x16x32_bf16 v[38:41], v[10:13], v[26:29], v[108:111]
	s_waitcnt lgkmcnt(2)
	v_mfma_f32_16x16x32_bf16 v[62:65], v[148:151], v[18:21], v[116:119]
	v_mfma_f32_16x16x32_bf16 v[34:37], v[148:151], v[26:29], v[124:127]
	v_mfma_f32_16x16x32_bf16 v[6:9], v[148:151], v[30:33], v[58:61]
	s_waitcnt lgkmcnt(0)
	v_mfma_f32_16x16x32_bf16 v[58:61], v[156:159], v[18:21], v[2:5]
	v_mfma_f32_16x16x32_bf16 v[18:21], v[156:159], v[26:29], v[128:131]
	v_bfe_u32 v167, v145, 2, 2
	v_lshrrev_b32_e32 v166, 2, v144
	v_lshl_or_b32 v167, v167, 2, v166
	v_sub_u32_e32 v164, v167, v145
	v_add_u32_e32 v164, v80, v164
	v_mov_b32_e32 v165, 0
	v_and_b32_e32 v166, 3, v145
	v_lshl_add_u32 v167, v166, 4, v167
	v_lshlrev_b32_e32 v167, 2, v167
	v_lshlrev_b32_e32 v166, 2, v166
	v_or_b32_e32 v28, s11, v164
	v_ashrrev_i32_e32 v29, 31, v28
	v_lshl_or_b32 v26, s10, 6, v166
	v_mfma_f32_16x16x32_bf16 v[50:53], v[10:13], v[22:25], v[92:95]
	v_ashrrev_i32_e32 v27, 31, v26
	v_lshlrev_b64 v[26:27], 1, v[26:27]
	s_ashr_i32 s10, s11, 31
	v_mfma_f32_16x16x32_bf16 v[10:13], v[10:13], v[30:33], v[112:115]
	v_mfma_f32_16x16x32_bf16 v[2:5], v[156:159], v[30:33], v[132:135]
	v_mov_b32_e32 v29, s10
	v_lshl_add_u64 v[28:29], v[28:29], 2, s[50:51]
	v_mfma_f32_16x16x32_bf16 v[46:49], v[148:151], v[22:25], v[120:123]
	v_mfma_f32_16x16x32_bf16 v[22:25], v[156:159], v[22:25], v[88:91]
	v_mov_b32_e32 v195, 0
	v_lshl_add_u64 v[196:197], s[52:53], 0, v[164:165]
	v_mad_u64_u32 v[200:201], s[20:21], v196, s64, v[82:83]
	v_mov_b32_e32 v198, v201
	v_mad_u64_u32 v[198:199], s[20:21], v197, s64, v[198:199]
	v_mov_b32_e32 v201, v198
	v_lshl_add_u64 v[200:201], v[200:201], 0, v[26:27]
	v_lshlrev_b64 v[196:197], 11, v[196:197]
	v_lshl_add_u64 v[208:209], s[70:71], 0, v[196:197]
	v_lshl_add_u64 v[208:209], v[208:209], 0, v[26:27]
	global_load_dword v216, v[28:29], off
	global_load_dwordx2 v[220:221], v[200:201], off offset:3584
	global_load_dwordx2 v[222:223], v[200:201], off offset:3616
	global_load_dwordx2 v[224:225], v[200:201], off offset:3648
	global_load_dwordx2 v[226:227], v[200:201], off offset:3680
	v_or_b32_e32 v194, 16, v164
	v_lshl_add_u64 v[196:197], s[52:53], 0, v[194:195]
	v_mad_u64_u32 v[202:203], s[20:21], v196, s64, v[82:83]
	v_mov_b32_e32 v198, v203
	v_mad_u64_u32 v[198:199], s[20:21], v197, s64, v[198:199]
	v_mov_b32_e32 v203, v198
	v_lshl_add_u64 v[202:203], v[202:203], 0, v[26:27]
	v_lshlrev_b64 v[196:197], 11, v[196:197]
	v_lshl_add_u64 v[210:211], s[70:71], 0, v[196:197]
	v_lshl_add_u64 v[210:211], v[210:211], 0, v[26:27]
	global_load_dword v217, v[28:29], off offset:64
	global_load_dwordx2 v[228:229], v[202:203], off offset:3584
	global_load_dwordx2 v[230:231], v[202:203], off offset:3616
	global_load_dwordx2 v[232:233], v[202:203], off offset:3648
	global_load_dwordx2 v[234:235], v[202:203], off offset:3680
	v_or_b32_e32 v194, 32, v164
	v_lshl_add_u64 v[196:197], s[52:53], 0, v[194:195]
	v_mad_u64_u32 v[204:205], s[20:21], v196, s64, v[82:83]
	v_mov_b32_e32 v198, v205
	v_mad_u64_u32 v[198:199], s[20:21], v197, s64, v[198:199]
	v_mov_b32_e32 v205, v198
	v_lshl_add_u64 v[204:205], v[204:205], 0, v[26:27]
	v_lshlrev_b64 v[196:197], 11, v[196:197]
	v_lshl_add_u64 v[212:213], s[70:71], 0, v[196:197]
	v_lshl_add_u64 v[212:213], v[212:213], 0, v[26:27]
	global_load_dword v218, v[28:29], off offset:128
	global_load_dwordx2 v[236:237], v[204:205], off offset:3584
	global_load_dwordx2 v[238:239], v[204:205], off offset:3616
	global_load_dwordx2 v[240:241], v[204:205], off offset:3648
	global_load_dwordx2 v[242:243], v[204:205], off offset:3680
	v_or_b32_e32 v194, 48, v164
	v_lshl_add_u64 v[196:197], s[52:53], 0, v[194:195]
	v_mad_u64_u32 v[206:207], s[20:21], v196, s64, v[82:83]
	v_mov_b32_e32 v198, v207
	v_mad_u64_u32 v[198:199], s[20:21], v197, s64, v[198:199]
	v_mov_b32_e32 v207, v198
	v_lshl_add_u64 v[206:207], v[206:207], 0, v[26:27]
	v_lshlrev_b64 v[196:197], 11, v[196:197]
	v_lshl_add_u64 v[214:215], s[70:71], 0, v[196:197]
	v_lshl_add_u64 v[214:215], v[214:215], 0, v[26:27]
	global_load_dword v219, v[28:29], off offset:192
	global_load_dwordx2 v[244:245], v[206:207], off offset:3584
	global_load_dwordx2 v[246:247], v[206:207], off offset:3616
	global_load_dwordx2 v[248:249], v[206:207], off offset:3648
	global_load_dwordx2 v[250:251], v[206:207], off offset:3680
	s_add_u32 s52, s52, s24
	s_addc_u32 s53, s53, s25
	ds_bpermute_b32 v2, v167, v2
	ds_bpermute_b32 v3, v167, v3
	ds_bpermute_b32 v4, v167, v4
	ds_bpermute_b32 v5, v167, v5
	ds_bpermute_b32 v6, v167, v6
	ds_bpermute_b32 v7, v167, v7
	ds_bpermute_b32 v8, v167, v8
	ds_bpermute_b32 v9, v167, v9
	s_waitcnt lgkmcnt(4)
	ds_bpermute_b32 v10, v167, v10
	ds_bpermute_b32 v11, v167, v11
	ds_bpermute_b32 v12, v167, v12
	ds_bpermute_b32 v13, v167, v13
	ds_bpermute_b32 v14, v167, v14
	ds_bpermute_b32 v15, v167, v15
	ds_bpermute_b32 v16, v167, v16
	ds_bpermute_b32 v17, v167, v17
	s_waitcnt lgkmcnt(4)
	ds_bpermute_b32 v18, v167, v18
	ds_bpermute_b32 v19, v167, v19
	ds_bpermute_b32 v20, v167, v20
	ds_bpermute_b32 v21, v167, v21
	ds_bpermute_b32 v22, v167, v22
	ds_bpermute_b32 v23, v167, v23
	ds_bpermute_b32 v24, v167, v24
	ds_bpermute_b32 v25, v167, v25
	s_waitcnt lgkmcnt(4)
	ds_bpermute_b32 v34, v167, v34
	ds_bpermute_b32 v35, v167, v35
	ds_bpermute_b32 v36, v167, v36
	ds_bpermute_b32 v37, v167, v37
	ds_bpermute_b32 v38, v167, v38
	ds_bpermute_b32 v39, v167, v39
	ds_bpermute_b32 v40, v167, v40
	ds_bpermute_b32 v41, v167, v41
	s_waitcnt lgkmcnt(4)
	ds_bpermute_b32 v42, v167, v42
	ds_bpermute_b32 v43, v167, v43
	ds_bpermute_b32 v44, v167, v44
	ds_bpermute_b32 v45, v167, v45
	ds_bpermute_b32 v46, v167, v46
	ds_bpermute_b32 v47, v167, v47
	ds_bpermute_b32 v48, v167, v48
	ds_bpermute_b32 v49, v167, v49
	s_waitcnt lgkmcnt(4)
	ds_bpermute_b32 v50, v167, v50
	ds_bpermute_b32 v51, v167, v51
	ds_bpermute_b32 v52, v167, v52
	ds_bpermute_b32 v53, v167, v53
	ds_bpermute_b32 v54, v167, v54
	ds_bpermute_b32 v55, v167, v55
	ds_bpermute_b32 v56, v167, v56
	ds_bpermute_b32 v57, v167, v57
	s_waitcnt lgkmcnt(4)
	ds_bpermute_b32 v58, v167, v58
	ds_bpermute_b32 v59, v167, v59
	ds_bpermute_b32 v60, v167, v60
	ds_bpermute_b32 v61, v167, v61
	ds_bpermute_b32 v62, v167, v62
	ds_bpermute_b32 v63, v167, v63
	ds_bpermute_b32 v64, v167, v64
	ds_bpermute_b32 v65, v167, v65
	s_waitcnt lgkmcnt(4)
	ds_bpermute_b32 v66, v167, v66
	ds_bpermute_b32 v67, v167, v67
	ds_bpermute_b32 v68, v167, v68
	ds_bpermute_b32 v69, v167, v69
	ds_bpermute_b32 v70, v167, v70
	ds_bpermute_b32 v71, v167, v71
	ds_bpermute_b32 v72, v167, v72
	ds_bpermute_b32 v73, v167, v73
	s_waitcnt lgkmcnt(4)
	s_waitcnt vmcnt(0) lgkmcnt(0)
	v_add_f32_e32 v70, v70, v216
	v_add_f32_e32 v71, v71, v216
	v_add_f32_e32 v72, v72, v216
	v_add_f32_e32 v73, v73, v216
	v_lshlrev_b32_e32 v194, 16, v220
	v_and_b32_e32 v195, 0xffff0000, v220
	v_lshlrev_b32_e32 v196, 16, v221
	v_and_b32_e32 v197, 0xffff0000, v221
	v_pk_mul_f32 v[70:71], v[70:71], v[194:195]
	v_pk_mul_f32 v[72:73], v[72:73], v[196:197]
	v_cvt_pk_bf16_f32 v70, v70, v71
	v_cvt_pk_bf16_f32 v71, v72, v73
	global_store_dwordx2 v[208:209], v[70:71], off offset:1536
	v_add_f32_e32 v66, v66, v216
	v_add_f32_e32 v67, v67, v216
	v_add_f32_e32 v68, v68, v216
	v_add_f32_e32 v69, v69, v216
	v_lshlrev_b32_e32 v194, 16, v222
	v_and_b32_e32 v195, 0xffff0000, v222
	v_lshlrev_b32_e32 v196, 16, v223
	v_and_b32_e32 v197, 0xffff0000, v223
	v_pk_mul_f32 v[66:67], v[66:67], v[194:195]
	v_pk_mul_f32 v[68:69], v[68:69], v[196:197]
	v_cvt_pk_bf16_f32 v66, v66, v67
	v_cvt_pk_bf16_f32 v67, v68, v69
	global_store_dwordx2 v[208:209], v[66:67], off offset:1568
	v_add_f32_e32 v62, v62, v216
	v_add_f32_e32 v63, v63, v216
	v_add_f32_e32 v64, v64, v216
	v_add_f32_e32 v65, v65, v216
	v_lshlrev_b32_e32 v194, 16, v224
	v_and_b32_e32 v195, 0xffff0000, v224
	v_lshlrev_b32_e32 v196, 16, v225
	v_and_b32_e32 v197, 0xffff0000, v225
	v_pk_mul_f32 v[62:63], v[62:63], v[194:195]
	v_pk_mul_f32 v[64:65], v[64:65], v[196:197]
	v_cvt_pk_bf16_f32 v62, v62, v63
	v_cvt_pk_bf16_f32 v63, v64, v65
	global_store_dwordx2 v[208:209], v[62:63], off offset:1600
	v_add_f32_e32 v58, v58, v216
	v_add_f32_e32 v59, v59, v216
	v_add_f32_e32 v60, v60, v216
	v_add_f32_e32 v61, v61, v216
	v_lshlrev_b32_e32 v194, 16, v226
	v_and_b32_e32 v195, 0xffff0000, v226
	v_lshlrev_b32_e32 v196, 16, v227
	v_and_b32_e32 v197, 0xffff0000, v227
	v_pk_mul_f32 v[58:59], v[58:59], v[194:195]
	v_pk_mul_f32 v[60:61], v[60:61], v[196:197]
	v_cvt_pk_bf16_f32 v58, v58, v59
	v_cvt_pk_bf16_f32 v59, v60, v61
	global_store_dwordx2 v[208:209], v[58:59], off offset:1632
	s_nop 0
	v_add_f32_e32 v54, v54, v217
	v_add_f32_e32 v55, v55, v217
	v_add_f32_e32 v56, v56, v217
	v_add_f32_e32 v57, v57, v217
	v_lshlrev_b32_e32 v194, 16, v228
	v_and_b32_e32 v195, 0xffff0000, v228
	v_lshlrev_b32_e32 v196, 16, v229
	v_and_b32_e32 v197, 0xffff0000, v229
	v_pk_mul_f32 v[54:55], v[54:55], v[194:195]
	v_pk_mul_f32 v[56:57], v[56:57], v[196:197]
	v_cvt_pk_bf16_f32 v54, v54, v55
	v_cvt_pk_bf16_f32 v55, v56, v57
	global_store_dwordx2 v[210:211], v[54:55], off offset:1536
	v_add_f32_e32 v50, v50, v217
	v_add_f32_e32 v51, v51, v217
	v_add_f32_e32 v52, v52, v217
	v_add_f32_e32 v53, v53, v217
	v_lshlrev_b32_e32 v194, 16, v230
	v_and_b32_e32 v195, 0xffff0000, v230
	v_lshlrev_b32_e32 v196, 16, v231
	v_and_b32_e32 v197, 0xffff0000, v231
	v_pk_mul_f32 v[50:51], v[50:51], v[194:195]
	v_pk_mul_f32 v[52:53], v[52:53], v[196:197]
	v_cvt_pk_bf16_f32 v50, v50, v51
	v_cvt_pk_bf16_f32 v51, v52, v53
	global_store_dwordx2 v[210:211], v[50:51], off offset:1568
	v_add_f32_e32 v46, v46, v217
	v_add_f32_e32 v47, v47, v217
	v_add_f32_e32 v48, v48, v217
	v_add_f32_e32 v49, v49, v217
	v_lshlrev_b32_e32 v194, 16, v232
	v_and_b32_e32 v195, 0xffff0000, v232
	v_lshlrev_b32_e32 v196, 16, v233
	v_and_b32_e32 v197, 0xffff0000, v233
	v_pk_mul_f32 v[46:47], v[46:47], v[194:195]
	v_pk_mul_f32 v[48:49], v[48:49], v[196:197]
	v_cvt_pk_bf16_f32 v46, v46, v47
	v_cvt_pk_bf16_f32 v47, v48, v49
	global_store_dwordx2 v[210:211], v[46:47], off offset:1600
	v_add_f32_e32 v22, v22, v217
	v_add_f32_e32 v23, v23, v217
	v_add_f32_e32 v24, v24, v217
	v_add_f32_e32 v25, v25, v217
	v_lshlrev_b32_e32 v194, 16, v234
	v_and_b32_e32 v195, 0xffff0000, v234
	v_lshlrev_b32_e32 v196, 16, v235
	v_and_b32_e32 v197, 0xffff0000, v235
	v_pk_mul_f32 v[22:23], v[22:23], v[194:195]
	v_pk_mul_f32 v[24:25], v[24:25], v[196:197]
	v_cvt_pk_bf16_f32 v22, v22, v23
	v_cvt_pk_bf16_f32 v23, v24, v25
	global_store_dwordx2 v[210:211], v[22:23], off offset:1632
	s_nop 0
	v_add_f32_e32 v42, v42, v218
	v_add_f32_e32 v43, v43, v218
	v_add_f32_e32 v44, v44, v218
	v_add_f32_e32 v45, v45, v218
	v_lshlrev_b32_e32 v194, 16, v236
	v_and_b32_e32 v195, 0xffff0000, v236
	v_lshlrev_b32_e32 v196, 16, v237
	v_and_b32_e32 v197, 0xffff0000, v237
	v_pk_mul_f32 v[42:43], v[42:43], v[194:195]
	v_pk_mul_f32 v[44:45], v[44:45], v[196:197]
	v_cvt_pk_bf16_f32 v42, v42, v43
	v_cvt_pk_bf16_f32 v43, v44, v45
	global_store_dwordx2 v[212:213], v[42:43], off offset:1536
	v_add_f32_e32 v38, v38, v218
	v_add_f32_e32 v39, v39, v218
	v_add_f32_e32 v40, v40, v218
	v_add_f32_e32 v41, v41, v218
	v_lshlrev_b32_e32 v194, 16, v238
	v_and_b32_e32 v195, 0xffff0000, v238
	v_lshlrev_b32_e32 v196, 16, v239
	v_and_b32_e32 v197, 0xffff0000, v239
	v_pk_mul_f32 v[38:39], v[38:39], v[194:195]
	v_pk_mul_f32 v[40:41], v[40:41], v[196:197]
	v_cvt_pk_bf16_f32 v38, v38, v39
	v_cvt_pk_bf16_f32 v39, v40, v41
	global_store_dwordx2 v[212:213], v[38:39], off offset:1568
	v_add_f32_e32 v34, v34, v218
	v_add_f32_e32 v35, v35, v218
	v_add_f32_e32 v36, v36, v218
	v_add_f32_e32 v37, v37, v218
	v_lshlrev_b32_e32 v194, 16, v240
	v_and_b32_e32 v195, 0xffff0000, v240
	v_lshlrev_b32_e32 v196, 16, v241
	v_and_b32_e32 v197, 0xffff0000, v241
	v_pk_mul_f32 v[34:35], v[34:35], v[194:195]
	v_pk_mul_f32 v[36:37], v[36:37], v[196:197]
	v_cvt_pk_bf16_f32 v34, v34, v35
	v_cvt_pk_bf16_f32 v35, v36, v37
	global_store_dwordx2 v[212:213], v[34:35], off offset:1600
	v_add_f32_e32 v18, v18, v218
	v_add_f32_e32 v19, v19, v218
	v_add_f32_e32 v20, v20, v218
	v_add_f32_e32 v21, v21, v218
	v_lshlrev_b32_e32 v194, 16, v242
	v_and_b32_e32 v195, 0xffff0000, v242
	v_lshlrev_b32_e32 v196, 16, v243
	v_and_b32_e32 v197, 0xffff0000, v243
	v_pk_mul_f32 v[18:19], v[18:19], v[194:195]
	v_pk_mul_f32 v[20:21], v[20:21], v[196:197]
	v_cvt_pk_bf16_f32 v18, v18, v19
	v_cvt_pk_bf16_f32 v19, v20, v21
	global_store_dwordx2 v[212:213], v[18:19], off offset:1632
	s_nop 0
	v_add_f32_e32 v14, v14, v219
	v_add_f32_e32 v15, v15, v219
	v_add_f32_e32 v16, v16, v219
	v_add_f32_e32 v17, v17, v219
	v_lshlrev_b32_e32 v194, 16, v244
	v_and_b32_e32 v195, 0xffff0000, v244
	v_lshlrev_b32_e32 v196, 16, v245
	v_and_b32_e32 v197, 0xffff0000, v245
	v_pk_mul_f32 v[14:15], v[14:15], v[194:195]
	v_pk_mul_f32 v[16:17], v[16:17], v[196:197]
	v_cvt_pk_bf16_f32 v14, v14, v15
	v_cvt_pk_bf16_f32 v15, v16, v17
	global_store_dwordx2 v[214:215], v[14:15], off offset:1536
	v_add_f32_e32 v10, v10, v219
	v_add_f32_e32 v11, v11, v219
	v_add_f32_e32 v12, v12, v219
	v_add_f32_e32 v13, v13, v219
	v_lshlrev_b32_e32 v194, 16, v246
	v_and_b32_e32 v195, 0xffff0000, v246
	v_lshlrev_b32_e32 v196, 16, v247
	v_and_b32_e32 v197, 0xffff0000, v247
	v_pk_mul_f32 v[10:11], v[10:11], v[194:195]
	v_pk_mul_f32 v[12:13], v[12:13], v[196:197]
	v_cvt_pk_bf16_f32 v10, v10, v11
	v_cvt_pk_bf16_f32 v11, v12, v13
	global_store_dwordx2 v[214:215], v[10:11], off offset:1568
	v_add_f32_e32 v6, v6, v219
	v_add_f32_e32 v7, v7, v219
	v_add_f32_e32 v8, v8, v219
	v_add_f32_e32 v9, v9, v219
	v_lshlrev_b32_e32 v194, 16, v248
	v_and_b32_e32 v195, 0xffff0000, v248
	v_lshlrev_b32_e32 v196, 16, v249
	v_and_b32_e32 v197, 0xffff0000, v249
	v_pk_mul_f32 v[6:7], v[6:7], v[194:195]
	v_pk_mul_f32 v[8:9], v[8:9], v[196:197]
	v_cvt_pk_bf16_f32 v6, v6, v7
	v_cvt_pk_bf16_f32 v7, v8, v9
	global_store_dwordx2 v[214:215], v[6:7], off offset:1600
	v_add_f32_e32 v2, v2, v219
	v_add_f32_e32 v3, v3, v219
	v_add_f32_e32 v4, v4, v219
	v_add_f32_e32 v5, v5, v219
	v_lshlrev_b32_e32 v194, 16, v250
	v_and_b32_e32 v195, 0xffff0000, v250
	v_lshlrev_b32_e32 v196, 16, v251
	v_and_b32_e32 v197, 0xffff0000, v251
	v_pk_mul_f32 v[2:3], v[2:3], v[194:195]
	v_pk_mul_f32 v[4:5], v[4:5], v[196:197]
	v_cvt_pk_bf16_f32 v2, v2, v3
	v_cvt_pk_bf16_f32 v3, v4, v5
	global_store_dwordx2 v[214:215], v[2:3], off offset:1632
	s_cmp_ge_i32 s16, s2
	s_barrier
	s_cbranch_scc0 .LBB0_257
	s_branch .LBB0_254
.LBB0_258:
	v_readlane_b32 s11, v254, 30
	s_mul_hi_u32 s10, s2, s11
	v_readlane_b32 s15, v254, 29
	s_mul_i32 s10, s10, s15
	s_sub_i32 s2, s2, s10
	s_add_i32 s3, s3, s96
	s_sub_i32 s10, s2, s15
	s_cmp_ge_u32 s2, s15
	s_cselect_b32 s2, s10, s2
	s_sub_i32 s10, s2, s15
	s_cmp_ge_u32 s2, s15
	s_cselect_b32 s2, s10, s2
	s_sub_i32 s2, s3, s2
	s_ashr_i32 s3, s2, 31
	s_abs_i32 s2, s2
	s_mul_hi_u32 s10, s2, s11
	s_mul_i32 s10, s10, s15
	s_sub_i32 s2, s2, s10
	s_sub_i32 s10, s2, s15
	s_cmp_ge_u32 s2, s15
	s_cselect_b32 s2, s10, s2
	s_sub_i32 s10, s2, s15
	s_cmp_ge_u32 s2, s15
	s_cselect_b32 s2, s10, s2
	s_xor_b32 s2, s2, s3
	s_sub_i32 s10, s2, s3
	v_readlane_b32 s2, v255, 36
	v_readlane_b32 s3, v255, 37
	s_lshl_b64 s[2:3], s[2:3], 2
	v_readlane_b32 s20, v255, 18
	v_readlane_b32 s21, v255, 19
	s_add_u32 s2, s20, s2
	s_addc_u32 s3, s21, s3
	s_add_i32 s10, s10, s57
	s_ashr_i32 s22, s10, 31
	s_abs_i32 s10, s10
	s_mul_hi_u32 s11, s10, s11
	s_mul_i32 s11, s11, s15
	s_sub_i32 s10, s10, s11
	s_sub_i32 s11, s10, s15
	s_cmp_ge_u32 s10, s15
	s_cselect_b32 s10, s11, s10
	s_sub_i32 s11, s10, s15
	s_cmp_ge_u32 s10, s15
	s_cselect_b32 s10, s11, s10
	s_xor_b32 s23, s10, s22
	s_sub_i32 s15, s23, s22
	s_sub_i32 s100, s15, s57
	s_and_b32 s100, s100, 0xff
	s_cmp_eq_u32 s100, 0
	s_cselect_b32 s100, s96, s100
	s_cmp_lt_i32 s15, s100
	s_cselect_b64 s[10:11], -1, 0
	s_lshl_b32 s16, s15, 5
	s_and_b32 s16, s16, 0xffffff80
	v_add_u32_e32 v0, s16, v139
	v_mov_b64_e32 v[2:3], s[72:73]
	s_lshl_b32 s16, s15, 7
	v_mad_i64_i32 v[2:3], s[20:21], v0, s64, v[2:3]
	s_and_b32 s16, s16, 0x180
	v_lshl_add_u64 v[2:3], v[2:3], 0, s[16:17]
	v_lshlrev_b32_e32 v0, 1, v142
	s_nop 0
	v_lshl_add_u64 v[30:31], v[2:3], 0, v[0:1]
	v_sub_u32_e32 v2, 0x7f, v139
	v_readlane_b32 s20, v255, 24
	v_cvt_f32_i32_e32 v36, v2
	v_lshlrev_b32_e32 v2, 2, v145
	v_mov_b32_e32 v3, v1
	v_readlane_b32 s21, v255, 25
	v_cvt_f32_i32_e32 v37, v139
	s_lshl_b32 s16, s23, 1
	v_lshl_add_u64 v[32:33], s[20:21], 0, v[2:3]
	s_lshl_b32 s20, s22, 1
	s_sub_i32 s20, s16, s20
	s_add_i32 s16, s100, s23
	v_mul_u32_u24_e32 v2, 0x90, v154
	s_sub_i32 s16, s16, s22
	v_lshlrev_b32_e32 v38, 8, v147
	v_add3_u32 v39, v2, v155, 0
	s_lshl_b32 s21, s16, 5
	s_lshl_b32 s28, s16, 6
	s_mov_b32 s29, 0
	s_branch .LBB0_260

.LBB0_709:
	s_waitcnt vmcnt(24)
	v_readlane_b32 s74, v254, 59
	v_readlane_b32 s44, v255, 38
	v_readlane_b32 s75, v254, 60
	v_readlane_b32 s46, v255, 45
	v_readlane_b32 s45, v255, 39
	v_readlane_b32 s47, v255, 42
	s_barrier

.LBB0_720:
	v_readlane_b32 s10, v253, 45
	s_waitcnt vmcnt(24)
	v_ashrrev_i32_e32 v2, 6, v140
	v_readlane_b32 s11, v253, 46
	s_andn2_b64 vcc, exec, s[10:11]
	v_readfirstlane_b32 s16, v2
	s_cbranch_vccnz .LBB0_725
	s_lshl_b32 s10, s47, 2
	v_readlane_b32 s11, v255, 20
	s_add_u32 s10, s11, s10
	s_addc_u32 s11, s56, 0
	s_add_u32 s10, s10, 0xc000
	s_addc_u32 s11, s11, 0
	s_lshr_b32 s15, s46, 8
	s_lshl_b32 s20, s46, 16
	v_readlane_b32 s21, v255, 32
	s_add_u32 s22, s21, s20
	v_readlane_b32 s20, v255, 30
	s_addc_u32 s23, s20, 0
	s_lshr_b32 s20, s46, 3
	s_mul_i32 s20, s16, s20
	s_ashr_i32 s21, s20, 31
	s_lshl_b64 s[20:21], s[20:21], 1
	s_add_u32 s22, s22, s20
	s_addc_u32 s23, s23, s21
	v_and_b32_e32 v0, 48, v192
	v_lshl_add_u64 v[34:35], s[22:23], 0, v[0:1]
	v_readlane_b32 s22, v255, 34
	s_add_u32 s20, s22, s20
	v_readlane_b32 s22, v255, 36
	s_addc_u32 s21, s22, s21
	v_lshl_add_u32 v53, v192, 4, 0
	v_lshl_add_u64 v[36:37], s[20:21], 0, v[0:1]
	v_and_b32_e32 v0, 0xfffffc0, v140
	v_lshl_add_u32 v55, v0, 4, v53
	v_ashrrev_i32_e32 v0, 4, v140
	s_lshl_b32 s20, s16, 13
	v_bfi_b32 v56, -16, v0, v140
	v_lshlrev_b32_e32 v0, 4, v2
	v_lshrrev_b32_e32 v2, 2, v192
	s_lshl_b32 s16, s46, 4
	v_and_b32_e32 v52, 15, v140
	s_lshl_b32 s22, s46, 5
	s_mov_b32 s23, s17
	v_lshl_add_u32 v54, v140, 4, 0
	v_bitop3_b32 v57, v0, 60, v2 bitop3:0xc8
	v_mov_b32_e32 v38, v142
	v_mov_b32_e32 v39, v142
	s_lshl_b32 s26, s16, 1
	s_mov_b32 s21, s57
